# r16 + XCC leaders poll the top barrier word back to back (s_sleep between polls removed)
# baseline (speedup 1.0000x reference)
.Lgb_tspin_s0:
	global_load_dword v1, v0, s[14:15] sc1
	s_waitcnt vmcnt(0)
	v_cmp_gt_u32_e32 vcc, s7, v1
	s_cbranch_vccz .Lgb_rel_s0
	s_branch .Lgb_tspin_s0
